# in_proj phase: the 64 workgroups whose last unit is a memKV unit (heavier epilogue) take no small piece; 64 other 4-unit workgroups take two
# speedup vs baseline: 1.0130x; 1.0130x over previous
.Lsp_long:
	s_cmpk_lt_u32 s0, 0x9c
	s_cbranch_scc1 .Lsp_long2
	s_mov_b32 s33, 0x7fffffff
	s_mov_b32 s32, 100
	s_branch .Lsp_init_done
.Lsp_long2:
	s_add_i32 s33, s0, 0x120
	s_mov_b32 s32, 100
	s_cmpk_lt_u32 s0, 0x40
	s_cbranch_scc0 .Lsp_init_done
	s_mov_b32 s32, 101

.LBB0_1211:
	s_cmp_eq_u32 s32, 0
	s_cbranch_scc1 .Lsp_std
	s_cmp_eq_u32 s32, 100
	s_cbranch_scc1 .Lsp_exit
	s_cmp_eq_u32 s32, 101
	s_cbranch_scc0 .Lsp_cnt
	s_add_i32 s33, s33, 0x9c
	s_mov_b32 s32, 100
	s_branch .Lsp_next
.Lsp_cnt:
	s_add_i32 s32, s32, 1
	s_cmpk_le_u32 s32, 8
	s_cbranch_scc0 .Lsp_ninth
	s_add_i32 s33, s33, 1
	s_branch .Lsp_next
